# row-norm loops (6 instances): gain-vector loads g[1..3] hoisted next to g[0] into borrowed dead VGPRs, per-load vmcnt(0) drains removed; on top of serial-chain + loop-edge + no-setprio + pipelined mem
# speedup vs baseline: 1.0085x; 1.0085x over previous
; __device__ __forceinline__ unsigned cvtpk(float lo, float hi) { unsigned r; asm volatile("v_cvt_pk_bf16_f32 %0, %1, %2" : "=v"(r) : "v"(lo), "v"(hi)); return r; }
; __device__ __forceinline__ void norm_row_bf16(const float* xrow, const float* g, bf16_t* orow, int lane) {
;   const f32x4* xr = (const f32x4*)xrow + lane; const f32x4* gr = (const f32x4*)g + lane;
;   f32x4 v[4]; float s = 0.f;
; #pragma unroll
;   for (int j = 0; j < 4; ++j) { v[j] = xr[64 * j]; s += (v[j].x * v[j].x + v[j].y * v[j].y) + (v[j].z * v[j].z + v[j].w * v[j].w); }
;   const float rinv = 1.0f / sqrtf(wave_sum(s) * (1.f / DM) + EPSN);
;   u32x2* o8 = (u32x2*)orow + lane;
; #pragma unroll
;   for (int j = 0; j < 4; ++j) { const f32x4 gg = gr[64 * j]; u32x2 w = {cvtpk(v[j].x * rinv * gg.x, v[j].y * rinv * gg.y), cvtpk(v[j].z * rinv * gg.z, v[j].w * rinv * gg.w)}; o8[64 * j] = w; }
; }
; __device__ __forceinline__ void phase_prologue(const Params& P, char* lds) {
;     ...
;   for (int row = gw; row < 2 * TB; row += NGW) norm_row_bf16(P.x + (size_t)row * DM, P.norm_g, (bf16_t*)(ws + OFF_HN) + (size_t)row * DM, lane);
.LBB0_52:
	global_load_dwordx4 v[16:19], v[12:13], off offset:-3072
	global_load_dwordx4 v[20:23], v[12:13], off offset:-2048
	global_load_dwordx4 v[24:27], v[12:13], off offset:-1024
	global_load_dwordx4 v[28:31], v[12:13], off
	global_load_dwordx4 v[32:35], v[4:5], off
	global_load_dwordx4 v[44:47], v[4:5], off offset:1024
	global_load_dwordx4 v[48:51], v[4:5], off offset:2048
	global_load_dwordx4 v[52:55], v[4:5], off offset:3072
	v_add_u32_e32 v9, s94, v9
	v_lshl_add_u64 v[12:13], v[12:13], 0, s[12:13]
	s_waitcnt vmcnt(4)
	v_mul_f32_e32 v14, v17, v17
	v_mul_f32_e32 v36, v19, v19
	s_waitcnt vmcnt(3)
	v_mul_f32_e32 v37, v21, v21
	v_mul_f32_e32 v38, v23, v23
	s_waitcnt vmcnt(2)
	v_mul_f32_e32 v39, v25, v25
	v_mul_f32_e32 v40, v27, v27
	v_fmac_f32_e32 v14, v16, v16
	v_fmac_f32_e32 v36, v18, v18
	v_fmac_f32_e32 v37, v20, v20
	v_fmac_f32_e32 v38, v22, v22
	s_waitcnt vmcnt(1)
	v_mul_f32_e32 v41, v29, v29
	v_mul_f32_e32 v42, v31, v31
	v_fmac_f32_e32 v39, v24, v24
	v_fmac_f32_e32 v40, v26, v26
	v_add_f32_e32 v14, v14, v36
	v_add_f32_e32 v36, v37, v38
	v_fmac_f32_e32 v41, v28, v28
	v_fmac_f32_e32 v42, v30, v30
	v_add_f32_e32 v37, v39, v40
	v_add_f32_e32 v14, v14, v36
	v_add_f32_e32 v38, v41, v42
	v_add_f32_e32 v14, v14, v37
	v_add_f32_e32 v14, v14, v38
	ds_swizzle_b32 v36, v14 offset:swizzle(SWAP,1)
	s_waitcnt lgkmcnt(0)
	v_add_f32_e32 v14, v14, v36
	ds_swizzle_b32 v36, v14 offset:swizzle(SWAP,2)
	s_waitcnt lgkmcnt(0)
	v_add_f32_e32 v14, v14, v36
	ds_swizzle_b32 v36, v14 offset:swizzle(SWAP,4)
	s_waitcnt lgkmcnt(0)
	v_add_f32_e32 v14, v14, v36
	ds_swizzle_b32 v36, v14 offset:swizzle(SWAP,8)
	s_waitcnt lgkmcnt(0)
	v_add_f32_e32 v14, v14, v36
	ds_swizzle_b32 v36, v14 offset:swizzle(SWAP,16)
	s_waitcnt lgkmcnt(0)
	v_add_f32_e32 v14, v14, v36
	v_mov_b32_e32 v36, v14
	s_nop 1
	v_permlane32_swap_b32_e32 v14, v36
	v_add_f32_e32 v14, v14, v36
	v_fmamk_f32 v14, v14, 0x3a800000, v3
	v_mul_f32_e32 v36, 0x4f800000, v14
	v_cmp_gt_f32_e32 vcc, s3, v14
	s_nop 1
	v_cndmask_b32_e32 v14, v14, v36, vcc
	v_sqrt_f32_e32 v36, v14
	s_nop 0
	v_add_u32_e32 v37, -1, v36
	v_add_u32_e32 v38, 1, v36
	v_fma_f32 v39, -v37, v36, v14
	v_fma_f32 v40, -v38, v36, v14
	v_cmp_ge_f32_e64 s[0:1], 0, v39
	s_nop 1
	v_cndmask_b32_e64 v36, v36, v37, s[0:1]
	v_cmp_lt_f32_e64 s[0:1], 0, v40
	s_nop 1
	v_cndmask_b32_e64 v36, v36, v38, s[0:1]
	v_mul_f32_e32 v37, 0x37800000, v36
	v_cndmask_b32_e32 v36, v36, v37, vcc
	v_cmp_class_f32_e32 vcc, v14, v7
	s_nop 1
	v_cndmask_b32_e32 v14, v36, v14, vcc
	v_div_scale_f32 v36, s[0:1], v14, v14, 1.0
	v_rcp_f32_e32 v38, v36
	v_div_scale_f32 v37, vcc, 1.0, v14, 1.0
	v_fma_f32 v39, -v36, v38, 1.0
	v_fmac_f32_e32 v38, v39, v38
	v_mul_f32_e32 v39, v37, v38
	v_fma_f32 v40, -v36, v39, v37
	v_fmac_f32_e32 v39, v40, v38
	v_fma_f32 v36, -v36, v39, v37
	v_div_fmas_f32 v36, v36, v38, v39
	v_div_fixup_f32 v14, v36, v14, 1.0
	v_mul_f32_e32 v16, v16, v14
	v_mul_f32_e32 v17, v17, v14
	v_mul_f32_e32 v18, v18, v14
	v_mul_f32_e32 v19, v19, v14
	s_waitcnt vmcnt(0)
	v_mul_f32_e32 v16, v32, v16
	v_mul_f32_e32 v17, v33, v17
	v_mul_f32_e32 v18, v34, v18
	v_mul_f32_e32 v19, v35, v19
	v_cvt_pk_bf16_f32 v16, v16, v17
	v_cvt_pk_bf16_f32 v17, v18, v19
	global_store_dwordx2 v[10:11], v[16:17], off
	v_mul_f32_e32 v20, v20, v14
	v_mul_f32_e32 v21, v21, v14
	v_mul_f32_e32 v22, v22, v14
	v_mul_f32_e32 v23, v23, v14
	v_cmp_lt_i32_e32 vcc, s16, v9
	s_or_b64 s[14:15], vcc, s[14:15]
	v_mul_f32_e32 v16, v44, v20
	v_mul_f32_e32 v17, v45, v21
	v_mul_f32_e32 v18, v46, v22
	v_mul_f32_e32 v19, v47, v23
	v_cvt_pk_bf16_f32 v16, v16, v17
	v_cvt_pk_bf16_f32 v17, v18, v19
	global_store_dwordx2 v[10:11], v[16:17], off offset:512
	v_mul_f32_e32 v20, v24, v14
	v_mul_f32_e32 v21, v25, v14
	v_mul_f32_e32 v22, v26, v14
	v_mul_f32_e32 v23, v27, v14
	v_mul_f32_e32 v16, v20, v48
	v_mul_f32_e32 v17, v21, v49
	v_mul_f32_e32 v18, v22, v50
	v_mul_f32_e32 v19, v23, v51
	v_cvt_pk_bf16_f32 v16, v16, v17
	v_cvt_pk_bf16_f32 v17, v18, v19
	global_store_dwordx2 v[10:11], v[16:17], off offset:1024
	v_mul_f32_e32 v20, v28, v14
	v_mul_f32_e32 v21, v29, v14
	v_mul_f32_e32 v22, v30, v14
	v_mul_f32_e32 v14, v31, v14
	v_mul_f32_e32 v16, v20, v52
	v_mul_f32_e32 v17, v21, v53
	v_mul_f32_e32 v18, v22, v54
	v_mul_f32_e32 v14, v14, v55
	v_cvt_pk_bf16_f32 v16, v16, v17
	v_cvt_pk_bf16_f32 v17, v18, v14
	global_store_dwordx2 v[10:11], v[16:17], off offset:1536
	v_lshl_add_u64 v[10:11], v[10:11], 0, s[6:7]
	s_andn2_b64 exec, exec, s[14:15]
	s_cbranch_execnz .LBB0_52

; __device__ __forceinline__ unsigned cvtpk(float lo, float hi) { unsigned r; asm volatile("v_cvt_pk_bf16_f32 %0, %1, %2" : "=v"(r) : "v"(lo), "v"(hi)); return r; }
; __device__ __forceinline__ void norm_row_bf16(const float* xrow, const float* g, bf16_t* orow, int lane) {
;   const f32x4* xr = (const f32x4*)xrow + lane; const f32x4* gr = (const f32x4*)g + lane;
;   f32x4 v[4]; float s = 0.f;
; #pragma unroll
;   for (int j = 0; j < 4; ++j) { v[j] = xr[64 * j]; s += (v[j].x * v[j].x + v[j].y * v[j].y) + (v[j].z * v[j].z + v[j].w * v[j].w); }
;   const float rinv = 1.0f / sqrtf(wave_sum(s) * (1.f / DM) + EPSN);
;   u32x2* o8 = (u32x2*)orow + lane;
; #pragma unroll
;   for (int j = 0; j < 4; ++j) { const f32x4 gg = gr[64 * j]; u32x2 w = {cvtpk(v[j].x * rinv * gg.x, v[j].y * rinv * gg.y), cvtpk(v[j].z * rinv * gg.z, v[j].w * rinv * gg.w)}; o8[64 * j] = w; }
; }
; __device__ __forceinline__ void phase_prologue(const Params& P, char* lds) {
;     ...
;   for (int it = gw; it < 1024; it += NGW) { const int l = it >> 9, row = it & 511;
;     norm_row_bf16(P.mem + (size_t)row * DM, P.mem_norm_g + l * DM, (bf16_t*)(ws + OFF_MN) + ((size_t)l * 512 + row) * DM, lane); }
.LBB0_55:
	v_and_b32_e32 v13, 0x1ff, v6
	v_lshlrev_b32_e32 v2, 12, v13
	v_lshl_add_u64 v[32:33], v[4:5], 0, v[2:3]
	global_load_dwordx4 v[16:19], v[32:33], off
	global_load_dwordx4 v[20:23], v[32:33], off offset:1024
	global_load_dwordx4 v[24:27], v[32:33], off offset:2048
	global_load_dwordx4 v[28:31], v[32:33], off offset:3072
	v_ashrrev_i32_e32 v32, 9, v6
	v_lshlrev_b32_e32 v36, 10, v32
	v_ashrrev_i32_e32 v33, 31, v32
	v_ashrrev_i32_e32 v37, 31, v36
	v_lshlrev_b64 v[32:33], 20, v[32:33]
	v_mov_b32_e32 v35, v3
	v_lshlrev_b32_e32 v34, 11, v13
	v_lshl_add_u64 v[32:33], s[6:7], 0, v[32:33]
	v_lshl_add_u64 v[36:37], v[36:37], 2, v[10:11]
	v_lshl_add_u64 v[38:39], v[32:33], 0, v[34:35]
	global_load_dwordx4 v[32:35], v[36:37], off
	global_load_dwordx4 v[48:51], v[36:37], off offset:1024
	global_load_dwordx4 v[52:55], v[36:37], off offset:2048
	global_load_dwordx4 v[56:59], v[36:37], off offset:3072
	v_lshl_add_u64 v[38:39], v[38:39], 0, v[8:9]
	v_add_u32_e32 v6, s94, v6
	s_waitcnt vmcnt(4)
	v_mul_f32_e32 v2, v17, v17
	v_mul_f32_e32 v13, v19, v19
	s_waitcnt vmcnt(3)
	v_mul_f32_e32 v14, v21, v21
	v_mul_f32_e32 v40, v23, v23
	s_waitcnt vmcnt(2)
	v_mul_f32_e32 v41, v25, v25
	v_mul_f32_e32 v42, v27, v27
	v_fmac_f32_e32 v2, v16, v16
	v_fmac_f32_e32 v13, v18, v18
	v_fmac_f32_e32 v14, v20, v20
	v_fmac_f32_e32 v40, v22, v22
	s_waitcnt vmcnt(1)
	v_mul_f32_e32 v43, v29, v29
	v_mul_f32_e32 v44, v31, v31
	v_fmac_f32_e32 v41, v24, v24
	v_fmac_f32_e32 v42, v26, v26
	v_add_f32_e32 v2, v2, v13
	v_add_f32_e32 v13, v14, v40
	v_fmac_f32_e32 v43, v28, v28
	v_fmac_f32_e32 v44, v30, v30
	v_add_f32_e32 v14, v41, v42
	v_add_f32_e32 v2, v2, v13
	v_add_f32_e32 v40, v43, v44
	v_add_f32_e32 v2, v2, v14
	v_add_f32_e32 v2, v2, v40
	ds_swizzle_b32 v13, v2 offset:swizzle(SWAP,1)
	s_waitcnt lgkmcnt(0)
	v_add_f32_e32 v2, v2, v13
	ds_swizzle_b32 v13, v2 offset:swizzle(SWAP,2)
	s_waitcnt lgkmcnt(0)
	v_add_f32_e32 v2, v2, v13
	ds_swizzle_b32 v13, v2 offset:swizzle(SWAP,4)
	s_waitcnt lgkmcnt(0)
	v_add_f32_e32 v2, v2, v13
	ds_swizzle_b32 v13, v2 offset:swizzle(SWAP,8)
	s_waitcnt lgkmcnt(0)
	v_add_f32_e32 v2, v2, v13
	ds_swizzle_b32 v13, v2 offset:swizzle(SWAP,16)
	s_waitcnt lgkmcnt(0)
	v_add_f32_e32 v2, v2, v13
	v_mov_b32_e32 v13, v2
	s_nop 1
	v_permlane32_swap_b32_e32 v2, v13
	v_add_f32_e32 v2, v2, v13
	v_fmamk_f32 v2, v2, 0x3a800000, v7
	v_mul_f32_e32 v13, 0x4f800000, v2
	v_cmp_gt_f32_e32 vcc, s3, v2
	s_nop 1
	v_cndmask_b32_e32 v2, v2, v13, vcc
	v_sqrt_f32_e32 v13, v2
	s_nop 0
	v_add_u32_e32 v14, -1, v13
	v_add_u32_e32 v40, 1, v13
	v_fma_f32 v41, -v14, v13, v2
	v_fma_f32 v42, -v40, v13, v2
	v_cmp_ge_f32_e64 s[0:1], 0, v41
	s_nop 1
	v_cndmask_b32_e64 v13, v13, v14, s[0:1]
	v_cmp_lt_f32_e64 s[0:1], 0, v42
	s_nop 1
	v_cndmask_b32_e64 v13, v13, v40, s[0:1]
	v_mul_f32_e32 v14, 0x37800000, v13
	v_cndmask_b32_e32 v13, v13, v14, vcc
	v_cmp_class_f32_e32 vcc, v2, v12
	s_nop 1
	v_cndmask_b32_e32 v2, v13, v2, vcc
	v_div_scale_f32 v13, s[0:1], v2, v2, 1.0
	v_rcp_f32_e32 v40, v13
	v_div_scale_f32 v14, vcc, 1.0, v2, 1.0
	v_fma_f32 v41, -v13, v40, 1.0
	v_fmac_f32_e32 v40, v41, v40
	v_mul_f32_e32 v41, v14, v40
	v_fma_f32 v42, -v13, v41, v14
	v_fmac_f32_e32 v41, v42, v40
	v_fma_f32 v13, -v13, v41, v14
	v_div_fmas_f32 v13, v13, v40, v41
	v_div_fixup_f32 v2, v13, v2, 1.0
	v_mul_f32_e32 v14, v17, v2
	v_mul_f32_e32 v17, v19, v2
	v_mul_f32_e32 v13, v16, v2
	v_mul_f32_e32 v16, v18, v2
	s_waitcnt vmcnt(0)
	v_mul_f32_e32 v17, v35, v17
	v_mul_f32_e32 v13, v32, v13
	v_mul_f32_e32 v14, v33, v14
	v_mul_f32_e32 v18, v34, v16
	v_cvt_pk_bf16_f32 v16, v13, v14
	v_cvt_pk_bf16_f32 v17, v18, v17
	global_store_dwordx2 v[38:39], v[16:17], off
	v_mul_f32_e32 v13, v20, v2
	v_mul_f32_e32 v14, v21, v2
	v_mul_f32_e32 v20, v22, v2
	v_mul_f32_e32 v21, v23, v2
	v_cmp_lt_i32_e32 vcc, s14, v6
	s_or_b64 s[12:13], vcc, s[12:13]
	v_mul_f32_e32 v14, v49, v14
	v_mul_f32_e32 v17, v50, v20
	v_mul_f32_e32 v13, v48, v13
	v_mul_f32_e32 v18, v51, v21
	v_cvt_pk_bf16_f32 v16, v13, v14
	v_cvt_pk_bf16_f32 v17, v17, v18
	global_store_dwordx2 v[38:39], v[16:17], off offset:512
	v_mul_f32_e32 v14, v25, v2
	v_mul_f32_e32 v20, v26, v2
	v_mul_f32_e32 v13, v24, v2
	v_mul_f32_e32 v21, v27, v2
	v_mul_f32_e32 v14, v14, v53
	v_mul_f32_e32 v17, v20, v54
	v_mul_f32_e32 v13, v13, v52
	v_mul_f32_e32 v18, v21, v55
	v_cvt_pk_bf16_f32 v16, v13, v14
	v_cvt_pk_bf16_f32 v17, v17, v18
	global_store_dwordx2 v[38:39], v[16:17], off offset:1024
	v_mul_f32_e32 v14, v29, v2
	v_mul_f32_e32 v20, v30, v2
	v_mul_f32_e32 v13, v28, v2
	v_mul_f32_e32 v2, v31, v2
	v_mul_f32_e32 v14, v14, v57
	v_mul_f32_e32 v17, v20, v58
	v_mul_f32_e32 v13, v13, v56
	v_mul_f32_e32 v2, v2, v59
	v_cvt_pk_bf16_f32 v16, v13, v14
	v_cvt_pk_bf16_f32 v17, v17, v2
	global_store_dwordx2 v[38:39], v[16:17], off offset:1536
	s_andn2_b64 exec, exec, s[12:13]
	s_cbranch_execnz .LBB0_55

; __device__ __forceinline__ unsigned cvtpk(float lo, float hi) { unsigned r; asm volatile("v_cvt_pk_bf16_f32 %0, %1, %2" : "=v"(r) : "v"(lo), "v"(hi)); return r; }
; __device__ __forceinline__ void norm_row_bf16(const float* xrow, const float* g, bf16_t* orow, int lane) {
;   const f32x4* xr = (const f32x4*)xrow + lane; const f32x4* gr = (const f32x4*)g + lane;
;   f32x4 v[4]; float s = 0.f;
; #pragma unroll
;   for (int j = 0; j < 4; ++j) { v[j] = xr[64 * j]; s += (v[j].x * v[j].x + v[j].y * v[j].y) + (v[j].z * v[j].z + v[j].w * v[j].w); }
;   const float rinv = 1.0f / sqrtf(wave_sum(s) * (1.f / DM) + EPSN);
;   u32x2* o8 = (u32x2*)orow + lane;
; #pragma unroll
;   for (int j = 0; j < 4; ++j) { const f32x4 gg = gr[64 * j]; u32x2 w = {cvtpk(v[j].x * rinv * gg.x, v[j].y * rinv * gg.y), cvtpk(v[j].z * rinv * gg.z, v[j].w * rinv * gg.w)}; o8[64 * j] = w; }
; }
; __device__ __forceinline__ void sweep_norm_bf16(const float* src, const float* g, bf16_t* dst, int row_lo, int row_hi) {
;   int tid = TIDX(); asm volatile("" : "+v"(tid));
;   const int wid = tid >> 6, lane = tid & 63;
;   for (int row = row_lo + blockIdx.x * 8 + wid; row < row_hi; row += gridDim.x * 8) norm_row_bf16(src + (size_t)row * DM, g, dst + (size_t)row * DM, lane);
; }
.LBB0_137:
	v_ashrrev_i32_e32 v1, 31, v0
	v_lshlrev_b64 v[8:9], 12, v[0:1]
	v_lshl_add_u64 v[20:21], v[2:3], 0, v[8:9]
	global_load_dwordx4 v[8:11], v[20:21], off
	global_load_dwordx4 v[12:15], v[20:21], off offset:1024
	global_load_dwordx4 v[16:19], v[20:21], off offset:2048
	s_nop 0
	global_load_dwordx4 v[20:23], v[20:21], off offset:3072
	s_nop 0
	global_load_dwordx4 v[24:27], v[4:5], off
	global_load_dwordx4 v[40:43], v[4:5], off offset:1024
	global_load_dwordx4 v[44:47], v[4:5], off offset:2048
	global_load_dwordx4 v[48:51], v[4:5], off offset:3072
	s_waitcnt vmcnt(0)
	v_mul_f32_e32 v28, v9, v9
	v_mul_f32_e32 v29, v11, v11
	s_waitcnt vmcnt(3)
	v_mul_f32_e32 v30, v13, v13
	v_mul_f32_e32 v31, v15, v15
	s_waitcnt vmcnt(2)
	v_mul_f32_e32 v32, v17, v17
	v_mul_f32_e32 v33, v19, v19
	v_fmac_f32_e32 v28, v8, v8
	v_fmac_f32_e32 v29, v10, v10
	v_fmac_f32_e32 v30, v12, v12
	v_fmac_f32_e32 v31, v14, v14
	s_waitcnt vmcnt(1)
	v_mul_f32_e32 v34, v21, v21
	v_mul_f32_e32 v35, v23, v23
	v_fmac_f32_e32 v32, v16, v16
	v_fmac_f32_e32 v33, v18, v18
	v_add_f32_e32 v28, v28, v29
	v_add_f32_e32 v29, v30, v31
	v_fmac_f32_e32 v34, v20, v20
	v_fmac_f32_e32 v35, v22, v22
	v_add_f32_e32 v30, v32, v33
	v_add_f32_e32 v28, v28, v29
	v_add_f32_e32 v31, v34, v35
	v_add_f32_e32 v28, v28, v30
	v_add_f32_e32 v28, v28, v31
	ds_swizzle_b32 v29, v28 offset:swizzle(SWAP,1)
	s_waitcnt lgkmcnt(0)
	v_add_f32_e32 v28, v28, v29
	ds_swizzle_b32 v29, v28 offset:swizzle(SWAP,2)
	s_waitcnt lgkmcnt(0)
	v_add_f32_e32 v28, v28, v29
	ds_swizzle_b32 v29, v28 offset:swizzle(SWAP,4)
	s_waitcnt lgkmcnt(0)
	v_add_f32_e32 v28, v28, v29
	ds_swizzle_b32 v29, v28 offset:swizzle(SWAP,8)
	s_waitcnt lgkmcnt(0)
	v_add_f32_e32 v28, v28, v29
	ds_swizzle_b32 v29, v28 offset:swizzle(SWAP,16)
	s_waitcnt lgkmcnt(0)
	v_add_f32_e32 v28, v28, v29
	v_mov_b32_e32 v29, v28
	s_nop 1
	v_permlane32_swap_b32_e32 v28, v29
	v_add_f32_e32 v28, v28, v29
	v_fmamk_f32 v28, v28, 0x3a800000, v163
	v_mul_f32_e32 v29, 0x4f800000, v28
	v_cmp_gt_f32_e32 vcc, s27, v28
	s_nop 1
	v_cndmask_b32_e32 v30, v28, v29, vcc
	v_sqrt_f32_e32 v31, v30
	v_lshlrev_b64 v[28:29], 11, v[0:1]
	v_lshl_add_u64 v[28:29], v[6:7], 0, v[28:29]
	v_add_u32_e32 v0, s94, v0
	v_add_u32_e32 v1, -1, v31
	v_add_u32_e32 v32, 1, v31
	v_fma_f32 v33, -v1, v31, v30
	v_fma_f32 v34, -v32, v31, v30
	v_cmp_ge_f32_e64 s[34:35], 0, v33
	s_nop 1
	v_cndmask_b32_e64 v1, v31, v1, s[34:35]
	v_cmp_lt_f32_e64 s[34:35], 0, v34
	s_nop 1
	v_cndmask_b32_e64 v1, v1, v32, s[34:35]
	v_mul_f32_e32 v31, 0x37800000, v1
	v_cndmask_b32_e32 v1, v1, v31, vcc
	v_cmp_class_f32_e32 vcc, v30, v204
	s_nop 1
	v_cndmask_b32_e32 v1, v1, v30, vcc
	v_div_scale_f32 v30, s[0:1], v1, v1, 1.0
	v_rcp_f32_e32 v31, v30
	v_div_scale_f32 v32, vcc, 1.0, v1, 1.0
	s_movk_i32 s0, 0x3fff
	v_fma_f32 v33, -v30, v31, 1.0
	v_fmac_f32_e32 v31, v33, v31
	v_mul_f32_e32 v33, v32, v31
	v_fma_f32 v34, -v30, v33, v32
	v_fmac_f32_e32 v33, v34, v31
	v_fma_f32 v30, -v30, v33, v32
	v_div_fmas_f32 v30, v30, v31, v33
	v_div_fixup_f32 v1, v30, v1, 1.0
	v_mul_f32_e32 v8, v8, v1
	v_mul_f32_e32 v9, v9, v1
	v_mul_f32_e32 v10, v10, v1
	v_mul_f32_e32 v11, v11, v1
	s_waitcnt vmcnt(0)
	v_mul_f32_e32 v8, v24, v8
	v_mul_f32_e32 v9, v25, v9
	v_mul_f32_e32 v10, v26, v10
	v_mul_f32_e32 v11, v27, v11
	v_cvt_pk_bf16_f32 v8, v8, v9
	v_cvt_pk_bf16_f32 v9, v10, v11
	global_store_dwordx2 v[28:29], v[8:9], off
	v_mul_f32_e32 v12, v12, v1
	v_mul_f32_e32 v13, v13, v1
	v_mul_f32_e32 v14, v14, v1
	v_mul_f32_e32 v15, v15, v1
	v_cmp_lt_i32_e32 vcc, s0, v0
	s_or_b64 s[18:19], vcc, s[18:19]
	v_mul_f32_e32 v8, v40, v12
	v_mul_f32_e32 v9, v41, v13
	v_mul_f32_e32 v10, v42, v14
	v_mul_f32_e32 v11, v43, v15
	v_cvt_pk_bf16_f32 v8, v8, v9
	v_cvt_pk_bf16_f32 v9, v10, v11
	global_store_dwordx2 v[28:29], v[8:9], off offset:512
	v_mul_f32_e32 v12, v16, v1
	v_mul_f32_e32 v13, v17, v1
	v_mul_f32_e32 v14, v18, v1
	v_mul_f32_e32 v15, v19, v1
	v_mul_f32_e32 v8, v12, v44
	v_mul_f32_e32 v9, v13, v45
	v_mul_f32_e32 v10, v14, v46
	v_mul_f32_e32 v11, v15, v47
	v_cvt_pk_bf16_f32 v8, v8, v9
	v_cvt_pk_bf16_f32 v9, v10, v11
	global_store_dwordx2 v[28:29], v[8:9], off offset:1024
	v_mul_f32_e32 v12, v20, v1
	v_mul_f32_e32 v13, v21, v1
	v_mul_f32_e32 v14, v22, v1
	v_mul_f32_e32 v1, v23, v1
	v_mul_f32_e32 v8, v12, v48
	v_mul_f32_e32 v9, v13, v49
	v_mul_f32_e32 v10, v14, v50
	v_mul_f32_e32 v1, v1, v51
	v_cvt_pk_bf16_f32 v8, v8, v9
	v_cvt_pk_bf16_f32 v9, v10, v1
	global_store_dwordx2 v[28:29], v[8:9], off offset:1536
	s_andn2_b64 exec, exec, s[18:19]
	s_cbranch_execnz .LBB0_137

; __device__ __forceinline__ void norm_row_f32(float* xrow, const float* g, int lane) {
;   f32x4* xr = (f32x4*)xrow + lane; const f32x4* gr = (const f32x4*)g + lane;
;   f32x4 v[4]; float s = 0.f;
; #pragma unroll
;   for (int j = 0; j < 4; ++j) { v[j] = xr[64 * j]; s += (v[j].x * v[j].x + v[j].y * v[j].y) + (v[j].z * v[j].z + v[j].w * v[j].w); }
;   const float rinv = 1.0f / sqrtf(wave_sum(s) * (1.f / DM) + EPSN);
; #pragma unroll
;   for (int j = 0; j < 4; ++j) { const f32x4 gg = gr[64 * j]; xr[64 * j] = v[j] * rinv * gg; }
; }
; __device__ __forceinline__ void sweep_norm_f32(float* src, const float* g, int row_lo, int row_hi) {
;   int tid = TIDX(); asm volatile("" : "+v"(tid));
;   const int wid = tid >> 6, lane = tid & 63;
;   for (int row = row_lo + blockIdx.x * 8 + wid; row < row_hi; row += gridDim.x * 8) norm_row_f32(src + (size_t)row * DM, g, lane);
; }
.LBB0_512:
	v_ashrrev_i32_e32 v23, 31, v22
	v_lshlrev_b64 v[2:3], 12, v[22:23]
	v_lshl_add_u64 v[28:29], v[24:25], 0, v[2:3]
	global_load_dwordx4 v[2:5], v[28:29], off
	v_add_u32_e32 v22, s94, v22
	s_waitcnt vmcnt(0)
	v_mul_f32_e32 v0, v3, v3
	v_mul_f32_e32 v6, v5, v5
	v_fmac_f32_e32 v0, v2, v2
	v_fmac_f32_e32 v6, v4, v4
	v_add_f32_e32 v0, v0, v6
	global_load_dwordx4 v[6:9], v[28:29], off offset:1024
	s_waitcnt vmcnt(0)
	v_mul_f32_e32 v10, v7, v7
	v_mul_f32_e32 v11, v9, v9
	v_fmac_f32_e32 v10, v6, v6
	v_fmac_f32_e32 v11, v8, v8
	v_add_f32_e32 v10, v10, v11
	v_add_f32_e32 v0, v0, v10
	global_load_dwordx4 v[10:13], v[28:29], off offset:2048
	s_waitcnt vmcnt(0)
	v_mul_f32_e32 v14, v11, v11
	v_mul_f32_e32 v15, v13, v13
	v_fmac_f32_e32 v14, v10, v10
	v_fmac_f32_e32 v15, v12, v12
	v_add_f32_e32 v14, v14, v15
	v_add_f32_e32 v0, v0, v14
	global_load_dwordx4 v[14:17], v[28:29], off offset:3072
	s_waitcnt vmcnt(0)
	v_mul_f32_e32 v18, v15, v15
	v_mul_f32_e32 v19, v17, v17
	v_fmac_f32_e32 v18, v14, v14
	v_fmac_f32_e32 v19, v16, v16
	v_add_f32_e32 v18, v18, v19
	v_add_f32_e32 v0, v0, v18
	ds_swizzle_b32 v18, v0 offset:swizzle(SWAP,1)
	s_waitcnt lgkmcnt(0)
	v_add_f32_e32 v0, v0, v18
	ds_swizzle_b32 v18, v0 offset:swizzle(SWAP,2)
	s_waitcnt lgkmcnt(0)
	v_add_f32_e32 v0, v0, v18
	ds_swizzle_b32 v18, v0 offset:swizzle(SWAP,4)
	s_waitcnt lgkmcnt(0)
	v_add_f32_e32 v0, v0, v18
	ds_swizzle_b32 v18, v0 offset:swizzle(SWAP,8)
	s_waitcnt lgkmcnt(0)
	v_add_f32_e32 v0, v0, v18
	ds_swizzle_b32 v18, v0 offset:swizzle(SWAP,16)
	s_waitcnt lgkmcnt(0)
	v_add_f32_e32 v0, v0, v18
	v_mov_b32_e32 v18, v0
	s_nop 1
	v_permlane32_swap_b32_e32 v0, v18
	v_add_f32_e32 v0, v0, v18
	v_fmamk_f32 v0, v0, 0x3a800000, v229
	v_cmp_gt_f32_e32 vcc, s87, v0
	v_mul_f32_e32 v18, 0x4f800000, v0
	s_nop 0
	v_cndmask_b32_e32 v0, v0, v18, vcc
	v_sqrt_f32_e32 v18, v0
	s_nop 0
	v_add_u32_e32 v19, -1, v18
	v_fma_f32 v20, -v19, v18, v0
	v_cmp_ge_f32_e64 s[38:39], 0, v20
	v_add_u32_e32 v20, 1, v18
	s_nop 0
	v_cndmask_b32_e64 v19, v18, v19, s[38:39]
	v_fma_f32 v18, -v20, v18, v0
	v_cmp_lt_f32_e64 s[38:39], 0, v18
	s_nop 1
	v_cndmask_b32_e64 v18, v19, v20, s[38:39]
	v_mul_f32_e32 v19, 0x37800000, v18
	v_cndmask_b32_e32 v18, v18, v19, vcc
	v_cmp_class_f32_e32 vcc, v0, v230
	s_nop 1
	v_cndmask_b32_e32 v0, v18, v0, vcc
	v_div_scale_f32 v18, s[0:1], v0, v0, 1.0
	v_rcp_f32_e32 v19, v18
	s_movk_i32 s0, 0x3fff
	v_fma_f32 v20, -v18, v19, 1.0
	v_fmac_f32_e32 v19, v20, v19
	v_div_scale_f32 v20, vcc, 1.0, v0, 1.0
	v_mul_f32_e32 v21, v20, v19
	v_fma_f32 v23, -v18, v21, v20
	v_fmac_f32_e32 v21, v23, v19
	v_fma_f32 v18, -v18, v21, v20
	v_div_fmas_f32 v18, v18, v19, v21
	v_div_fixup_f32 v0, v18, v0, 1.0
	global_load_dwordx4 v[18:21], v[26:27], off
	global_load_dwordx4 v[40:43], v[26:27], off offset:1024
	global_load_dwordx4 v[44:47], v[26:27], off offset:2048
	global_load_dwordx4 v[48:51], v[26:27], off offset:3072
	v_pk_mul_f32 v[2:3], v[2:3], v[0:1] op_sel_hi:[1,0]
	v_pk_mul_f32 v[4:5], v[4:5], v[0:1] op_sel_hi:[1,0]
	v_pk_mul_f32 v[8:9], v[8:9], v[0:1] op_sel_hi:[1,0]
	v_pk_mul_f32 v[6:7], v[6:7], v[0:1] op_sel_hi:[1,0]
	v_cmp_lt_i32_e32 vcc, s0, v22
	s_or_b64 s[24:25], vcc, s[24:25]
	s_waitcnt vmcnt(0)
	v_pk_mul_f32 v[4:5], v[20:21], v[4:5]
	v_pk_mul_f32 v[2:3], v[18:19], v[2:3]
	global_store_dwordx4 v[28:29], v[2:5], off
	s_nop 1
	v_pk_mul_f32 v[2:3], v[40:41], v[6:7]
	v_pk_mul_f32 v[4:5], v[42:43], v[8:9]
	global_store_dwordx4 v[28:29], v[2:5], off offset:1024
	v_pk_mul_f32 v[6:7], v[12:13], v[0:1] op_sel_hi:[1,0]
	v_pk_mul_f32 v[8:9], v[10:11], v[0:1] op_sel_hi:[1,0]
	v_pk_mul_f32 v[4:5], v[46:47], v[6:7]
	v_pk_mul_f32 v[2:3], v[44:45], v[8:9]
	global_store_dwordx4 v[28:29], v[2:5], off offset:2048
	v_pk_mul_f32 v[6:7], v[16:17], v[0:1] op_sel_hi:[1,0]
	v_pk_mul_f32 v[8:9], v[14:15], v[0:1] op_sel_hi:[1,0]
	v_pk_mul_f32 v[4:5], v[50:51], v[6:7]
	v_pk_mul_f32 v[2:3], v[48:49], v[8:9]
	global_store_dwordx4 v[28:29], v[2:5], off offset:3072
	s_andn2_b64 exec, exec, s[24:25]
	s_cbranch_execnz .LBB0_512

; __device__ __forceinline__ unsigned cvtpk(float lo, float hi) { unsigned r; asm volatile("v_cvt_pk_bf16_f32 %0, %1, %2" : "=v"(r) : "v"(lo), "v"(hi)); return r; }
; __device__ __forceinline__ void norm_row_bf16(const float* xrow, const float* g, bf16_t* orow, int lane) {
;   const f32x4* xr = (const f32x4*)xrow + lane; const f32x4* gr = (const f32x4*)g + lane;
;   f32x4 v[4]; float s = 0.f;
; #pragma unroll
;   for (int j = 0; j < 4; ++j) { v[j] = xr[64 * j]; s += (v[j].x * v[j].x + v[j].y * v[j].y) + (v[j].z * v[j].z + v[j].w * v[j].w); }
;   const float rinv = 1.0f / sqrtf(wave_sum(s) * (1.f / DM) + EPSN);
;   u32x2* o8 = (u32x2*)orow + lane;
; #pragma unroll
;   for (int j = 0; j < 4; ++j) { const f32x4 gg = gr[64 * j]; u32x2 w = {cvtpk(v[j].x * rinv * gg.x, v[j].y * rinv * gg.y), cvtpk(v[j].z * rinv * gg.z, v[j].w * rinv * gg.w)}; o8[64 * j] = w; }
; }
; __device__ __forceinline__ void sweep_norm_bf16(const float* src, const float* g, bf16_t* dst, int row_lo, int row_hi) {
;   int tid = TIDX(); asm volatile("" : "+v"(tid));
;   const int wid = tid >> 6, lane = tid & 63;
;   for (int row = row_lo + blockIdx.x * 8 + wid; row < row_hi; row += gridDim.x * 8) norm_row_bf16(src + (size_t)row * DM, g, dst + (size_t)row * DM, lane);
; }
.LBB0_517:
	v_ashrrev_i32_e32 v23, 31, v22
	v_lshlrev_b64 v[2:3], 12, v[22:23]
	v_lshl_add_u64 v[6:7], v[24:25], 0, v[2:3]
	global_load_dwordx4 v[14:17], v[6:7], off
	global_load_dwordx4 v[10:13], v[6:7], off offset:1024
	s_waitcnt vmcnt(0)
	v_mul_f32_e32 v0, v15, v15
	v_mul_f32_e32 v2, v17, v17
	v_fmac_f32_e32 v0, v14, v14
	v_fmac_f32_e32 v2, v16, v16
	v_add_f32_e32 v0, v0, v2
	s_waitcnt vmcnt(0)
	v_mul_f32_e32 v2, v11, v11
	v_mul_f32_e32 v3, v13, v13
	v_fmac_f32_e32 v2, v10, v10
	v_fmac_f32_e32 v3, v12, v12
	v_add_f32_e32 v2, v2, v3
	v_add_f32_e32 v0, v0, v2
	global_load_dwordx4 v[2:5], v[6:7], off offset:2048
	s_waitcnt vmcnt(0)
	v_mul_f32_e32 v8, v3, v3
	v_mul_f32_e32 v9, v5, v5
	v_fmac_f32_e32 v8, v2, v2
	v_fmac_f32_e32 v9, v4, v4
	v_add_f32_e32 v8, v8, v9
	v_add_f32_e32 v0, v0, v8
	global_load_dwordx4 v[6:9], v[6:7], off offset:3072
	s_waitcnt vmcnt(0)
	v_mul_f32_e32 v18, v7, v7
	v_mul_f32_e32 v19, v9, v9
	v_fmac_f32_e32 v18, v6, v6
	v_fmac_f32_e32 v19, v8, v8
	v_add_f32_e32 v18, v18, v19
	v_add_f32_e32 v0, v0, v18
	ds_swizzle_b32 v18, v0 offset:swizzle(SWAP,1)
	s_waitcnt lgkmcnt(0)
	v_add_f32_e32 v0, v0, v18
	ds_swizzle_b32 v18, v0 offset:swizzle(SWAP,2)
	s_waitcnt lgkmcnt(0)
	v_add_f32_e32 v0, v0, v18
	ds_swizzle_b32 v18, v0 offset:swizzle(SWAP,4)
	s_waitcnt lgkmcnt(0)
	v_add_f32_e32 v0, v0, v18
	ds_swizzle_b32 v18, v0 offset:swizzle(SWAP,8)
	s_waitcnt lgkmcnt(0)
	v_add_f32_e32 v0, v0, v18
	ds_swizzle_b32 v18, v0 offset:swizzle(SWAP,16)
	s_waitcnt lgkmcnt(0)
	v_add_f32_e32 v0, v0, v18
	v_mov_b32_e32 v18, v0
	s_nop 1
	v_permlane32_swap_b32_e32 v0, v18
	v_add_f32_e32 v0, v0, v18
	v_fmamk_f32 v0, v0, 0x3a800000, v229
	v_cmp_gt_f32_e32 vcc, s87, v0
	v_mul_f32_e32 v18, 0x4f800000, v0
	s_nop 0
	v_cndmask_b32_e32 v0, v0, v18, vcc
	v_sqrt_f32_e32 v18, v0
	s_nop 0
	v_add_u32_e32 v19, -1, v18
	v_fma_f32 v20, -v19, v18, v0
	v_cmp_ge_f32_e64 s[38:39], 0, v20
	v_add_u32_e32 v20, 1, v18
	s_nop 0
	v_cndmask_b32_e64 v19, v18, v19, s[38:39]
	v_fma_f32 v18, -v20, v18, v0
	v_cmp_lt_f32_e64 s[38:39], 0, v18
	s_nop 1
	v_cndmask_b32_e64 v18, v19, v20, s[38:39]
	v_mul_f32_e32 v19, 0x37800000, v18
	v_cndmask_b32_e32 v18, v18, v19, vcc
	v_cmp_class_f32_e32 vcc, v0, v230
	s_nop 1
	v_cndmask_b32_e32 v0, v18, v0, vcc
	v_div_scale_f32 v18, s[0:1], v0, v0, 1.0
	v_rcp_f32_e32 v19, v18
	s_movk_i32 s0, 0x7fff
	v_fma_f32 v20, -v18, v19, 1.0
	v_fmac_f32_e32 v19, v20, v19
	v_div_scale_f32 v20, vcc, 1.0, v0, 1.0
	v_mul_f32_e32 v21, v20, v19
	v_fma_f32 v30, -v18, v21, v20
	v_fmac_f32_e32 v21, v30, v19
	v_fma_f32 v18, -v18, v21, v20
	v_div_fmas_f32 v18, v18, v19, v21
	v_div_fixup_f32 v0, v18, v0, 1.0
	v_lshlrev_b64 v[18:19], 11, v[22:23]
	v_lshl_add_u64 v[30:31], v[28:29], 0, v[18:19]
	global_load_dwordx4 v[18:21], v[26:27], off
	global_load_dwordx4 v[40:43], v[26:27], off offset:1024
	global_load_dwordx4 v[44:47], v[26:27], off offset:2048
	global_load_dwordx4 v[48:51], v[26:27], off offset:3072
	v_mul_f32_e32 v14, v14, v0
	v_mul_f32_e32 v15, v15, v0
	v_mul_f32_e32 v10, v10, v0
	v_mul_f32_e32 v11, v11, v0
	v_mul_f32_e32 v2, v2, v0
	v_mul_f32_e32 v3, v3, v0
	v_mul_f32_e32 v6, v6, v0
	v_add_u32_e32 v22, s94, v22
	v_cmp_lt_i32_e32 vcc, s0, v22
	s_or_b64 s[24:25], vcc, s[24:25]
	s_waitcnt vmcnt(0)
	v_mul_f32_e32 v14, v18, v14
	v_mul_f32_e32 v15, v19, v15
	v_cvt_pk_bf16_f32 v14, v14, v15
	v_mul_f32_e32 v15, v16, v0
	v_mul_f32_e32 v15, v20, v15
	v_mul_f32_e32 v16, v17, v0
	v_mul_f32_e32 v16, v21, v16
	v_cvt_pk_bf16_f32 v15, v15, v16
	global_store_dwordx2 v[30:31], v[14:15], off
	v_mul_f32_e32 v10, v40, v10
	v_mul_f32_e32 v11, v41, v11
	v_cvt_pk_bf16_f32 v10, v10, v11
	v_mul_f32_e32 v11, v12, v0
	v_mul_f32_e32 v11, v42, v11
	v_mul_f32_e32 v12, v13, v0
	v_mul_f32_e32 v12, v43, v12
	v_cvt_pk_bf16_f32 v11, v11, v12
	global_store_dwordx2 v[30:31], v[10:11], off offset:512
	v_mul_f32_e32 v2, v2, v44
	v_mul_f32_e32 v3, v3, v45
	v_cvt_pk_bf16_f32 v2, v2, v3
	v_mul_f32_e32 v3, v4, v0
	v_mul_f32_e32 v3, v3, v46
	v_mul_f32_e32 v4, v5, v0
	v_mul_f32_e32 v4, v4, v47
	v_cvt_pk_bf16_f32 v3, v3, v4
	global_store_dwordx2 v[30:31], v[2:3], off offset:1024
	v_mul_f32_e32 v2, v6, v48
	v_mul_f32_e32 v6, v7, v0
	v_mul_f32_e32 v3, v6, v49
	v_cvt_pk_bf16_f32 v2, v2, v3
	v_mul_f32_e32 v3, v8, v0
	v_mul_f32_e32 v3, v3, v50
	v_mul_f32_e32 v0, v9, v0
	v_mul_f32_e32 v0, v0, v51
	v_cvt_pk_bf16_f32 v3, v3, v0
	global_store_dwordx2 v[30:31], v[2:3], off offset:1536
	s_andn2_b64 exec, exec, s[24:25]
	s_cbranch_execnz .LBB0_517

; __device__ __forceinline__ void norm_row_f32(float* xrow, const float* g, int lane) {
;   f32x4* xr = (f32x4*)xrow + lane; const f32x4* gr = (const f32x4*)g + lane;
;   f32x4 v[4]; float s = 0.f;
; #pragma unroll
;   for (int j = 0; j < 4; ++j) { v[j] = xr[64 * j]; s += (v[j].x * v[j].x + v[j].y * v[j].y) + (v[j].z * v[j].z + v[j].w * v[j].w); }
;   const float rinv = 1.0f / sqrtf(wave_sum(s) * (1.f / DM) + EPSN);
; #pragma unroll
;   for (int j = 0; j < 4; ++j) { const f32x4 gg = gr[64 * j]; xr[64 * j] = v[j] * rinv * gg; }
; }
; __global__ void __launch_bounds__(512, 2) mega(Params P) {
;     ...
;   sweep_norm_f32(P.out, P.final_g, TB, 2 * TB);
.LBB0_820:
	v_ashrrev_i32_e32 v1, 31, v0
	v_lshlrev_b64 v[8:9], 12, v[0:1]
	v_lshl_add_u64 v[28:29], v[2:3], 0, v[8:9]
	global_load_dwordx4 v[8:11], v[28:29], off
	global_load_dwordx4 v[12:15], v[28:29], off offset:1024
	global_load_dwordx4 v[16:19], v[28:29], off offset:2048
	global_load_dwordx4 v[20:23], v[28:29], off offset:3072
	global_load_dwordx4 v[24:27], v[4:5], off
	global_load_dwordx4 v[40:43], v[4:5], off offset:1024
	global_load_dwordx4 v[44:47], v[4:5], off offset:2048
	global_load_dwordx4 v[48:51], v[4:5], off offset:3072
	v_add_u32_e32 v0, s94, v0
	s_waitcnt vmcnt(0)
	v_mul_f32_e32 v1, v9, v9
	v_mul_f32_e32 v30, v11, v11
	v_mul_f32_e32 v31, v13, v13
	v_mul_f32_e32 v32, v15, v15
	v_mul_f32_e32 v33, v17, v17
	v_mul_f32_e32 v34, v19, v19
	v_fmac_f32_e32 v1, v8, v8
	v_fmac_f32_e32 v30, v10, v10
	v_fmac_f32_e32 v31, v12, v12
	v_fmac_f32_e32 v32, v14, v14
	v_mul_f32_e32 v35, v21, v21
	v_mul_f32_e32 v36, v23, v23
	v_fmac_f32_e32 v33, v16, v16
	v_fmac_f32_e32 v34, v18, v18
	v_add_f32_e32 v1, v1, v30
	v_add_f32_e32 v30, v31, v32
	v_fmac_f32_e32 v35, v20, v20
	v_fmac_f32_e32 v36, v22, v22
	v_add_f32_e32 v31, v33, v34
	v_add_f32_e32 v1, v1, v30
	v_add_f32_e32 v32, v35, v36
	v_add_f32_e32 v1, v1, v31
	v_add_f32_e32 v1, v1, v32
	ds_swizzle_b32 v30, v1 offset:swizzle(SWAP,1)
	s_waitcnt lgkmcnt(0)
	v_add_f32_e32 v1, v1, v30
	ds_swizzle_b32 v30, v1 offset:swizzle(SWAP,2)
	s_waitcnt lgkmcnt(0)
	v_add_f32_e32 v1, v1, v30
	ds_swizzle_b32 v30, v1 offset:swizzle(SWAP,4)
	s_waitcnt lgkmcnt(0)
	v_add_f32_e32 v1, v1, v30
	ds_swizzle_b32 v30, v1 offset:swizzle(SWAP,8)
	s_waitcnt lgkmcnt(0)
	v_add_f32_e32 v1, v1, v30
	ds_swizzle_b32 v30, v1 offset:swizzle(SWAP,16)
	s_waitcnt lgkmcnt(0)
	v_add_f32_e32 v1, v1, v30
	v_mov_b32_e32 v30, v1
	s_nop 1
	v_permlane32_swap_b32_e32 v1, v30
	v_add_f32_e32 v1, v1, v30
	v_fmamk_f32 v1, v1, 0x3a800000, v6
	v_mul_f32_e32 v30, 0x4f800000, v1
	v_cmp_gt_f32_e32 vcc, s4, v1
	s_nop 1
	v_cndmask_b32_e32 v1, v1, v30, vcc
	v_sqrt_f32_e32 v30, v1
	s_nop 0
	v_add_u32_e32 v31, -1, v30
	v_add_u32_e32 v32, 1, v30
	v_fma_f32 v33, -v31, v30, v1
	v_fma_f32 v34, -v32, v30, v1
	v_cmp_ge_f32_e64 s[0:1], 0, v33
	s_nop 1
	v_cndmask_b32_e64 v30, v30, v31, s[0:1]
	v_cmp_lt_f32_e64 s[0:1], 0, v34
	s_nop 1
	v_cndmask_b32_e64 v30, v30, v32, s[0:1]
	v_mul_f32_e32 v31, 0x37800000, v30
	v_cndmask_b32_e32 v30, v30, v31, vcc
	v_cmp_class_f32_e32 vcc, v1, v7
	s_nop 1
	v_cndmask_b32_e32 v1, v30, v1, vcc
	v_div_scale_f32 v30, s[0:1], v1, v1, 1.0
	v_rcp_f32_e32 v31, v30
	v_div_scale_f32 v32, vcc, 1.0, v1, 1.0
	v_fma_f32 v33, -v30, v31, 1.0
	v_fmac_f32_e32 v31, v33, v31
	v_mul_f32_e32 v33, v32, v31
	v_fma_f32 v34, -v30, v33, v32
	v_fmac_f32_e32 v33, v34, v31
	v_fma_f32 v30, -v30, v33, v32
	v_div_fmas_f32 v30, v30, v31, v33
	v_div_fixup_f32 v30, v30, v1, 1.0
	v_pk_mul_f32 v[8:9], v[8:9], v[30:31] op_sel_hi:[1,0]
	v_pk_mul_f32 v[10:11], v[10:11], v[30:31] op_sel_hi:[1,0]
	v_pk_mul_f32 v[8:9], v[24:25], v[8:9]
	v_pk_mul_f32 v[10:11], v[26:27], v[10:11]
	global_store_dwordx4 v[28:29], v[8:11], off
	v_pk_mul_f32 v[14:15], v[14:15], v[30:31] op_sel_hi:[1,0]
	v_pk_mul_f32 v[12:13], v[12:13], v[30:31] op_sel_hi:[1,0]
	v_cmp_lt_i32_e32 vcc, s5, v0
	s_or_b64 s[2:3], vcc, s[2:3]
	v_pk_mul_f32 v[8:9], v[40:41], v[12:13]
	v_pk_mul_f32 v[10:11], v[42:43], v[14:15]
	global_store_dwordx4 v[28:29], v[8:11], off offset:1024
	v_pk_mul_f32 v[12:13], v[18:19], v[30:31] op_sel_hi:[1,0]
	v_pk_mul_f32 v[14:15], v[16:17], v[30:31] op_sel_hi:[1,0]
	v_pk_mul_f32 v[10:11], v[46:47], v[12:13]
	v_pk_mul_f32 v[8:9], v[44:45], v[14:15]
	global_store_dwordx4 v[28:29], v[8:11], off offset:2048
	v_pk_mul_f32 v[12:13], v[22:23], v[30:31] op_sel_hi:[1,0]
	v_pk_mul_f32 v[14:15], v[20:21], v[30:31] op_sel_hi:[1,0]
	v_pk_mul_f32 v[10:11], v[50:51], v[12:13]
	v_pk_mul_f32 v[8:9], v[48:49], v[14:15]
	global_store_dwordx4 v[28:29], v[8:11], off offset:3072
	s_andn2_b64 exec, exec, s[2:3]
	s_cbranch_execnz .LBB0_820
